# xcd_barrier: non-leader workgroups poll the cross-XCC generation word directly (no second release hop through the per-XCC generation)
# baseline (speedup 1.0000x reference)
; __device__ __forceinline__ unsigned xb_ld(unsigned* p)              { return __hip_atomic_load(p, __ATOMIC_RELAXED, __HIP_MEMORY_SCOPE_AGENT); }
; __device__ __forceinline__ unsigned xb_add(unsigned* p, unsigned v) { return __hip_atomic_fetch_add(p, v, __ATOMIC_RELAXED, __HIP_MEMORY_SCOPE_AGENT); }
; #define XB_SPIN(cond, bar) do { unsigned _sp = 0; while (cond) { __builtin_amdgcn_s_sleep(1); \
;     if ((++_sp & 255u) == 0u) { if (xb_ld(&(bar)[XB_TMO])) break; if (_sp > XB_SPIN_CAP) { atomicAdd(&(bar)[XB_TMO], 1u); break; } } } } while (0)
; __device__ __forceinline__ void xcd_barrier(const XcdBarrier& b) {
;     ...
;         const unsigned old = xb_add(&bar[XB_XSUB(b.x)], 1u);
;         const unsigned gen = old / nloc;
;         if (old + 1u == (gen + 1u) * nloc) {
;             __builtin_amdgcn_fence(__ATOMIC_RELEASE, "agent");
;             asm volatile("s_waitcnt vmcnt(0)" ::: "memory");
;             const unsigned og = xb_add(&bar[XB_TOP], 1u);
;             const unsigned tg = og / nx;
;             if (og + 1u == (tg + 1u) * nx) xb_add(&bar[XB_TOPGEN], 1u);
;             else XB_SPIN(xb_ld(&bar[XB_TOPGEN]) == tg, bar);
;             __builtin_amdgcn_fence(__ATOMIC_ACQUIRE, "agent");
;             xb_add(&bar[XB_XGEN(b.x)], 1u);
;             asm volatile("s_waitcnt vmcnt(0)" ::: "memory");
;         } else {
;             XB_SPIN(xb_ld(&bar[XB_XGEN(b.x)]) == gen, bar);
;             __builtin_amdgcn_fence(__ATOMIC_ACQUIRE, "agent");
;             asm volatile("s_waitcnt vmcnt(0)" ::: "memory");
;         }
.LBB0_556:
	s_or_b64 exec, exec, s[8:9]
	v_cvt_f32_u32_e32 v4, v2
	s_waitcnt vmcnt(0)
	v_readfirstlane_b32 s8, v3
	v_sub_u32_e32 v3, 0, v2
	v_rcp_iflag_f32_e32 v4, v4
	v_add_u32_e32 v5, s8, v1
	v_mul_f32_e32 v4, 0x4f7ffffe, v4
	v_cvt_u32_f32_e32 v4, v4
	v_mul_lo_u32 v1, v3, v4
	v_mul_hi_u32 v1, v4, v1
	v_add_u32_e32 v1, v4, v1
	v_mul_hi_u32 v1, v5, v1
	v_mul_lo_u32 v3, v1, v2
	v_sub_u32_e32 v3, v5, v3
	v_add_u32_e32 v4, 1, v1
	v_cmp_ge_u32_e32 vcc, v3, v2
	s_nop 1
	v_cndmask_b32_e32 v1, v1, v4, vcc
	v_sub_u32_e32 v4, v3, v2
	v_cndmask_b32_e32 v3, v3, v4, vcc
	v_add_u32_e32 v4, 1, v1
	v_cmp_ge_u32_e32 vcc, v3, v2
	v_add_u32_e32 v3, 1, v5
	s_nop 0
	v_cndmask_b32_e32 v1, v1, v4, vcc
	v_mul_lo_u32 v4, v2, v1
	v_add_u32_e32 v2, v4, v2
	v_cmp_ne_u32_e32 vcc, v3, v2
	s_and_saveexec_b64 s[8:9], vcc
	s_xor_b64 s[8:9], exec, s[8:9]
	s_cbranch_execz .LBB0_570
	v_readlane_b32 s10, v254, 13
	v_readlane_b32 s11, v254, 14
	s_waitcnt lgkmcnt(0)
	s_nop 3
	global_load_dword v0, v49, s[10:11] sc1
	s_waitcnt vmcnt(0)
	v_cmp_eq_u32_e32 vcc, v0, v1
	s_and_saveexec_b64 s[10:11], vcc
	s_cbranch_execz .LBB0_569
	s_mov_b32 s24, 1
	s_mov_b64 s[12:13], 0
	s_branch .LBB0_560

; __device__ __forceinline__ unsigned xb_ld(unsigned* p)              { return __hip_atomic_load(p, __ATOMIC_RELAXED, __HIP_MEMORY_SCOPE_AGENT); }
; #define XB_SPIN(cond, bar) do { unsigned _sp = 0; while (cond) { __builtin_amdgcn_s_sleep(1); \
;     if ((++_sp & 255u) == 0u) { if (xb_ld(&(bar)[XB_TMO])) break; if (_sp > XB_SPIN_CAP) { atomicAdd(&(bar)[XB_TMO], 1u); break; } } } } while (0)
; __device__ __forceinline__ void xcd_barrier(const XcdBarrier& b) {
;     ...
;             XB_SPIN(xb_ld(&bar[XB_XGEN(b.x)]) == gen, bar);
.LBB0_562:
	v_readlane_b32 s18, v254, 13
	v_readlane_b32 s19, v254, 14
	s_add_i32 s24, s24, 1
	s_mov_b64 s[20:21], -1
	s_nop 2
	global_load_dword v0, v49, s[18:19] sc1
	s_waitcnt vmcnt(0)
	v_cmp_ne_u32_e32 vcc, v0, v1
	s_orn2_b64 s[18:19], vcc, exec
	s_branch .LBB0_559
